# GEMM K-loops: per-phase s_setprio toggles removed, one static priority raise for the wave half that runs a barrier behind (wr=1)
# speedup vs baseline: 1.0188x; 1.0188x over previous
; #define PG8_STAGE(bufoff, gbase, voff) do { _Pragma("unroll") for (int _i = 0; _i < 2; ++_i) \
;         __builtin_amdgcn_global_load_lds((const unsigned*)((const char*)(gbase) + (voff)[_i]), (LAS unsigned*)(lds + (bufoff) + ldsw + _i * 8192), 16, 0, 0); } while (0)
; #define PG8_WAIT_V(n) asm volatile("s_waitcnt vmcnt(" #n ")" ::: "memory")
; #define PG8_BAR __builtin_amdgcn_s_barrier()
; template <class Epi>
; __device__ __forceinline__ void gemm_phase(LAS unsigned char* lds, const Gemm g, const StaticOrder& S, const Epi& E) {
;     const int tid = threadIdx.x, wid = __builtin_amdgcn_readfirstlane(tid >> 6), lane = tid & 63, wr = wid >> 2, wc = wid & 3, fr = lane & 15, fq = lane >> 4;
;     const int K = g.K, nt = K / BK;
;     unsigned voffA[2], voffB[2];
; #pragma unroll
;     for (int i = 0; i < 2; ++i) { int R, C; stage_rc(tid * 16 + i * 8192, R, C); const int Rb = Epi::PERM ? ((R & ~31) + perm32(R & 31)) : R;
;         voffA[i] = (unsigned)(R * K + C) * 2u; voffB[i] = (unsigned)(Rb * K + C) * 2u; }
;     const size_t kstep = (size_t)(BK * 2);
;     const size_t hstep = (size_t)HALF * K * 2;
;     const size_t tstep = 2 * hstep;
;     const unsigned ldsw = (unsigned)wid * 1024u;
;     const int aoff = lds_byte(wr * 64 + fr, fq * 8), boff = lds_byte(wc * 32 + fr, fq * 8);
;     ...
;     Unit cur, nxt; int ui = 0;
;     if (!S.next(0, cur)) return;
;     f32x4 acc[2][2][4][2];
; #pragma unroll
;     for (int a = 0; a < 2; ++a)
; #pragma unroll
;         for (int b = 0; b < 2; ++b)
; #pragma unroll
;             for (int m = 0; m < 4; ++m)
; #pragma unroll
;                 for (int n = 0; n < 2; ++n) acc[a][b][m][n] = (f32x4){0.f, 0.f, 0.f, 0.f};
;     bf16x8 At[4][2], B0[2][2], B1[2][2];
;     const char* cA = (const char*)g.A + (size_t)cur.pm * tstep; const char* cB = (const char*)g.Bt + (size_t)cur.pn * tstep;
;     PG8_STAGE(PG8_SB(0, 0), cB, voffB); PG8_STAGE(PG8_SA(0, 0), cA, voffA); PG8_STAGE(PG8_SB(0, 1), cB + hstep, voffB); PG8_STAGE(PG8_SA(0, 1), cA + hstep, voffA);
;     if (wr == 1) PG8_BAR;
;     PG8_WAIT_V(4); PG8_BAR;
;     PG8_STAGE(PG8_SB(1, 0), cB + kstep, voffB); PG8_STAGE(PG8_SA(1, 0), cA + kstep, voffA); PG8_STAGE(PG8_SB(1, 1), cB + hstep + kstep, voffB);
;     PG8_WAIT_V(6); PG8_BAR;
.LBB0_72:
	v_lshrrev_b32_e32 v165, 1, v133
	v_and_b32_e32 v158, 24, v165
	v_lshlrev_b32_e32 v0, 6, v133
	v_lshlrev_b32_e32 v162, 1, v158
	v_and_b32_e32 v0, 0x3c0, v0
	v_and_b32_e32 v1, 32, v134
	s_mov_b32 s2, s40
	v_readfirstlane_b32 s34, v133
	v_and_b32_e32 v161, 15, v133
	v_bitop3_b32 v163, v162, v1, v0 bitop3:0x36
	s_cmpk_gt_i32 s40, 0xf67
	v_bfe_u32 v168, v133, 2, 2
	v_bfe_u32 v160, v133, 2, 4
	v_lshrrev_b32_e32 v169, 5, v133
	v_lshlrev_b32_e32 v166, 4, v133
	v_and_b32_e32 v167, 32, v133
	v_and_b32_e32 v159, 64, v133
	v_lshrrev_b32_e32 v164, 3, v133
	v_writelane_b32 v244, s2, 6
	s_nop 1
	v_writelane_b32 v244, s3, 7
	s_cbranch_scc1 .LBB0_96
	v_and_b32_e32 v0, 4, v169
	v_and_b32_e32 v1, 24, v165
	v_add_u32_e32 v8, 0x2000, v166
	v_or3_b32 v0, v0, v168, v1
	v_lshrrev_b32_e32 v1, 7, v8
	s_movk_i32 s6, 0xe0
	v_and_or_b32 v2, v1, s6, v0
	s_movk_i32 s6, 0xf0
	v_bitop3_b32 v9, v166, v167, 48 bitop3:0x6c
	v_and_or_b32 v1, v1, s6, v160
	s_movk_i32 s6, 0x60
	v_or_b32_e32 v3, v9, v159
	v_and_or_b32 v0, v164, s6, v0
	s_movk_i32 s6, 0x70
	s_mov_b32 s8, s40
	s_ashr_i32 s40, s40, 31
	v_lshl_or_b32 v140, v0, 12, v3
	v_and_or_b32 v0, v164, s6, v160
	s_lshr_b32 s6, s40, 29
	s_add_i32 s6, s8, s6
	s_lshr_b32 s9, s34, 6
	s_ashr_i32 s7, s6, 3
	s_and_b32 s6, s6, -8
	s_lshr_b32 s10, s34, 8
	s_lshl_b32 s35, s9, 10
	s_sub_i32 s6, s8, s6
	s_cmp_lt_i32 s6, 0
	s_movk_i32 s41, 0x1ee
	s_cselect_b32 s8, s41, 0x1ed
	s_mul_i32 s6, s8, s6
	s_add_i32 s6, s6, s7
	s_mul_hi_i32 s7, s6, 0x8d3dcb09
	s_add_i32 s7, s7, s6
	s_lshr_b32 s8, s7, 31
	s_ashr_i32 s7, s7, 7
	s_add_i32 s7, s7, s8
	s_lshl_b32 s11, s7, 3
	s_mulk_i32 s7, 0xe8
	s_sub_i32 s6, s6, s7
	s_sext_i32_i16 s7, s6
	s_bfe_u32 s7, s7, 0x3001c
	s_add_i32 s7, s6, s7
	s_sext_i32_i16 s8, s7
	s_and_b32 s7, s7, 0xfff8
	s_load_dwordx2 s[2:3], s[0:1], 0xc0
	s_load_dwordx2 s[4:5], s[0:1], 0xd0
	s_sub_i32 s6, s6, s7
	s_sext_i32_i16 s6, s6
	s_lshr_b32 s8, s8, 3
	s_add_i32 s6, s11, s6
	s_ashr_i32 s7, s6, 31
	s_bfe_i64 s[14:15], s[8:9], 0x100000
	s_lshl_b64 s[12:13], s[6:7], 20
	s_lshl_b64 s[14:15], s[14:15], 20
	s_waitcnt lgkmcnt(0)
	s_add_u32 s18, s4, s14
	s_addc_u32 s19, s5, s15
	s_add_i32 s42, s35, 0
	s_add_i32 m0, s42, 0x10000
	v_lshl_or_b32 v136, v2, 12, v3
	global_load_lds_dwordx4 v140, s[18:19]
	s_add_i32 m0, s42, 0x12000
	s_add_u32 s20, s2, s12
	v_lshl_or_b32 v142, v0, 12, v3
	global_load_lds_dwordx4 v136, s[18:19]
	s_addc_u32 s21, s3, s13
	s_mov_b32 m0, s42
	s_add_i32 s43, s42, 0x2000
	v_lshl_or_b32 v138, v1, 12, v3
	global_load_lds_dwordx4 v142, s[20:21]
	s_mov_b32 m0, s43
	s_add_u32 s12, s18, 0x80000
	global_load_lds_dwordx4 v138, s[20:21]
	s_addc_u32 s13, s19, 0
	s_add_i32 m0, s42, 0x14000
	v_mov_b32_e32 v145, 0
	global_load_lds_dwordx4 v140, s[12:13]
	s_add_i32 m0, s42, 0x16000
	v_mov_b32_e32 v141, v145
	global_load_lds_dwordx4 v136, s[12:13]
	s_add_u32 s12, s20, 0x80000
	s_addc_u32 s13, s21, 0
	s_add_i32 s44, s42, 0x4000
	s_mov_b32 m0, s44
	s_add_i32 s45, s42, 0x6000
	global_load_lds_dwordx4 v142, s[12:13]
	s_mov_b32 m0, s45
	v_mov_b32_e32 v137, v145
	global_load_lds_dwordx4 v138, s[12:13]
	s_load_dwordx4 s[12:15], s[0:1], 0xb0
	v_mov_b32_e32 v143, v145
	v_mov_b32_e32 v139, v145
	s_mov_b32 s46, 0
	v_lshl_add_u64 v[6:7], s[18:19], 0, v[140:141]
	v_lshl_add_u64 v[4:5], s[18:19], 0, v[136:137]
	v_lshl_add_u64 v[2:3], s[20:21], 0, v[142:143]
	s_cmp_lg_u32 s10, 1
	v_lshl_add_u64 v[0:1], s[20:21], 0, v[138:139]
	s_cbranch_scc1 .LBB0_75
	s_setprio 1
	s_barrier

; #define PG8_STAGE(bufoff, gbase, voff) do { _Pragma("unroll") for (int _i = 0; _i < 2; ++_i) \
;         __builtin_amdgcn_global_load_lds((const unsigned*)((const char*)(gbase) + (voff)[_i]), (LAS unsigned*)(lds + (bufoff) + ldsw + _i * 8192), 16, 0, 0); } while (0)
; #define PG8_LDA(dst, b, h) do { _Pragma("unroll") for (int m = 0; m < 4; ++m) _Pragma("unroll") for (int k = 0; k < 2; ++k) dst[m][k] = *(const LAS bf16x8*)(lds + PG8_SA(b, h) + aoff + m * 2048 + k * 1024); } while (0)
; #define PG8_LDB(dst, b, h) do { _Pragma("unroll") for (int n = 0; n < 2; ++n) _Pragma("unroll") for (int k = 0; k < 2; ++k) dst[n][k] = *(const LAS bf16x8*)(lds + PG8_SB(b, h) + boff + n * 2048 + k * 1024); } while (0)
; #define PG8_MMA(ai, bj, At, Bt) do { __builtin_amdgcn_s_setprio(1); _Pragma("unroll") for (int m = 0; m < 4; ++m) _Pragma("unroll") for (int n = 0; n < 2; ++n) _Pragma("unroll") for (int k = 0; k < 2; ++k) \
;         acc[ai][bj][m][n] = __builtin_amdgcn_mfma_f32_16x16x32_bf16(Bt[n][k], At[m][k], acc[ai][bj][m][n], 0, 0, 0); __builtin_amdgcn_s_setprio(0); } while (0)
; #define PG8_WAIT_L(n) asm volatile("s_waitcnt lgkmcnt(" #n ")" ::: "memory")
; #define PG8_BAR __builtin_amdgcn_s_barrier()
; #define PG8_SCHED __builtin_amdgcn_sched_barrier(0)
; template <class Epi>
; __device__ __forceinline__ void gemm_phase(LAS unsigned char* lds, const Gemm g, const StaticOrder& S, const Epi& E) {
;     ...
;             PG8_LDB(B0, 0, 0); PG8_SCHED; PG8_LDA(At, 0, 0); PG8_STAGE(PG8_SA(1, 1), a1 + hstep, voffA);
;             PG8_WAIT_L(8); PG8_BAR; PG8_WAIT_L(0); PG8_MMA(0, 0, At, B0); PG8_BAR; PG8_SCHED;
;             PG8_LDB(B1, 0, 1); PG8_STAGE(PG8_SB(0, 0), b2, voffB);
;             PG8_BAR; PG8_WAIT_L(0); PG8_MMA(0, 1, At, B1); PG8_BAR;
;             PG8_LDA(At, 0, 1); PG8_STAGE(PG8_SA(0, 0), a2, voffA);
;             PG8_BAR; PG8_WAIT_L(0); PG8_MMA(1, 0, At, B0); PG8_BAR; PG8_SCHED;
.LBB0_80:
	ds_read_b128 v[154:157], v173
	ds_read_b128 v[176:179], v173 offset:1024
	ds_read_b128 v[180:183], v173 offset:2048
	ds_read_b128 v[184:187], v173 offset:3072
	s_add_u32 s26, s12, 0xfff80080
	s_addc_u32 s27, s13, -1
	s_cmp_eq_u32 s67, 28
	s_cselect_b32 s29, s7, s27
	s_cselect_b32 s28, s63, s26
	s_cselect_b32 s27, s25, s66
	s_cselect_b32 s26, s64, s65
	v_lshl_add_u64 v[220:221], s[12:13], 0, v[146:147]
	s_add_i32 m0, s42, 0xc000
	ds_read_b128 v[188:191], v174
	ds_read_b128 v[192:195], v174 offset:1024
	ds_read_b128 v[196:199], v174 offset:2048
	ds_read_b128 v[200:203], v174 offset:3072
	ds_read_b128 v[204:207], v174 offset:4096
	ds_read_b128 v[208:211], v174 offset:5120
	ds_read_b128 v[212:215], v174 offset:6144
	ds_read_b128 v[216:219], v174 offset:7168
	global_load_lds_dwordx4 v[220:221], off
	v_lshl_add_u64 v[220:221], s[12:13], 0, v[148:149]
	s_add_i32 m0, s42, 0xe000
	s_nop 0
	global_load_lds_dwordx4 v[220:221], off
	s_waitcnt lgkmcnt(8)
	s_barrier
	s_waitcnt lgkmcnt(0)
	s_waitcnt lgkmcnt(0)
	v_mfma_f32_16x16x32_bf16 v[124:127], v[154:157], v[188:191], v[124:127]
	v_mfma_f32_16x16x32_bf16 v[120:123], v[180:183], v[188:191], v[120:123]
	v_mfma_f32_16x16x32_bf16 v[116:119], v[154:157], v[196:199], v[116:119]
	v_mfma_f32_16x16x32_bf16 v[112:115], v[180:183], v[196:199], v[112:115]
	v_mfma_f32_16x16x32_bf16 v[100:103], v[154:157], v[204:207], v[100:103]
	v_mfma_f32_16x16x32_bf16 v[96:99], v[180:183], v[204:207], v[96:99]
	v_mfma_f32_16x16x32_bf16 v[76:79], v[154:157], v[212:215], v[76:79]
	v_mfma_f32_16x16x32_bf16 v[72:75], v[180:183], v[212:215], v[72:75]
	v_mfma_f32_16x16x32_bf16 v[124:127], v[176:179], v[192:195], v[124:127]
	v_mfma_f32_16x16x32_bf16 v[120:123], v[184:187], v[192:195], v[120:123]
	v_mfma_f32_16x16x32_bf16 v[116:119], v[176:179], v[200:203], v[116:119]
	v_mfma_f32_16x16x32_bf16 v[112:115], v[184:187], v[200:203], v[112:115]
	v_mfma_f32_16x16x32_bf16 v[100:103], v[176:179], v[208:211], v[100:103]
	v_mfma_f32_16x16x32_bf16 v[96:99], v[184:187], v[208:211], v[96:99]
	v_mfma_f32_16x16x32_bf16 v[76:79], v[176:179], v[216:219], v[76:79]
	v_mfma_f32_16x16x32_bf16 v[72:75], v[184:187], v[216:219], v[72:75]
	s_barrier
	s_add_i32 s68, s55, s35
	v_lshl_add_u64 v[236:237], s[26:27], 0, v[140:141]
	s_mov_b32 m0, s68
	ds_read_b128 v[220:223], v175
	ds_read_b128 v[224:227], v175 offset:1024
	ds_read_b128 v[228:231], v175 offset:2048
	ds_read_b128 v[232:235], v175 offset:3072
	global_load_lds_dwordx4 v[236:237], off
	v_lshl_add_u64 v[238:239], s[26:27], 0, v[136:137]
	s_add_i32 m0, s68, 0x2000
	s_nop 0
	global_load_lds_dwordx4 v[238:239], off
	s_barrier
	s_waitcnt lgkmcnt(0)
	s_waitcnt lgkmcnt(0)
	v_mfma_f32_16x16x32_bf16 v[108:111], v[220:223], v[188:191], v[108:111]
	v_mfma_f32_16x16x32_bf16 v[104:107], v[228:231], v[188:191], v[104:107]
	v_mfma_f32_16x16x32_bf16 v[92:95], v[220:223], v[196:199], v[92:95]
	v_mfma_f32_16x16x32_bf16 v[88:91], v[228:231], v[196:199], v[88:91]
	v_mfma_f32_16x16x32_bf16 v[84:87], v[220:223], v[204:207], v[84:87]
	v_mfma_f32_16x16x32_bf16 v[80:83], v[228:231], v[204:207], v[80:83]
	v_mfma_f32_16x16x32_bf16 v[68:71], v[220:223], v[212:215], v[68:71]
	v_mfma_f32_16x16x32_bf16 v[64:67], v[228:231], v[212:215], v[64:67]
	v_mfma_f32_16x16x32_bf16 v[108:111], v[224:227], v[192:195], v[108:111]
	v_mfma_f32_16x16x32_bf16 v[104:107], v[232:235], v[192:195], v[104:107]
	v_mfma_f32_16x16x32_bf16 v[92:95], v[224:227], v[200:203], v[92:95]
	v_mfma_f32_16x16x32_bf16 v[88:91], v[232:235], v[200:203], v[88:91]
	v_mfma_f32_16x16x32_bf16 v[84:87], v[224:227], v[208:211], v[84:87]
	v_mfma_f32_16x16x32_bf16 v[80:83], v[232:235], v[208:211], v[80:83]
	v_mfma_f32_16x16x32_bf16 v[68:71], v[224:227], v[216:219], v[68:71]
	v_mfma_f32_16x16x32_bf16 v[64:67], v[232:235], v[216:219], v[64:67]
	s_mov_b32 m0, s42
	v_lshl_add_u64 v[240:241], s[28:29], 0, v[142:143]
	s_barrier
	ds_read_b128 v[188:191], v174 offset:16384
	ds_read_b128 v[192:195], v174 offset:17408
	ds_read_b128 v[196:199], v174 offset:18432
	ds_read_b128 v[200:203], v174 offset:19456
	ds_read_b128 v[204:207], v174 offset:20480
	ds_read_b128 v[208:211], v174 offset:21504
	ds_read_b128 v[212:215], v174 offset:22528
	ds_read_b128 v[216:219], v174 offset:23552
	global_load_lds_dwordx4 v[240:241], off
	v_lshl_add_u64 v[242:243], s[28:29], 0, v[138:139]
	s_mov_b32 m0, s43
	s_nop 0
	global_load_lds_dwordx4 v[242:243], off
	s_barrier
	s_waitcnt lgkmcnt(0)
	s_waitcnt lgkmcnt(0)
	v_mfma_f32_16x16x32_bf16 v[60:63], v[154:157], v[188:191], v[60:63]
	v_mfma_f32_16x16x32_bf16 v[56:59], v[180:183], v[188:191], v[56:59]
	v_mfma_f32_16x16x32_bf16 v[52:55], v[154:157], v[196:199], v[52:55]
	v_mfma_f32_16x16x32_bf16 v[48:51], v[180:183], v[196:199], v[48:51]
	v_mfma_f32_16x16x32_bf16 v[36:39], v[154:157], v[204:207], v[36:39]
	v_mfma_f32_16x16x32_bf16 v[32:35], v[180:183], v[204:207], v[32:35]
	v_mfma_f32_16x16x32_bf16 v[12:15], v[154:157], v[212:215], v[12:15]
	v_mfma_f32_16x16x32_bf16 v[8:11], v[180:183], v[212:215], v[8:11]
	v_mfma_f32_16x16x32_bf16 v[60:63], v[176:179], v[192:195], v[60:63]
	v_mfma_f32_16x16x32_bf16 v[56:59], v[184:187], v[192:195], v[56:59]
	v_mfma_f32_16x16x32_bf16 v[52:55], v[176:179], v[200:203], v[52:55]
	v_mfma_f32_16x16x32_bf16 v[48:51], v[184:187], v[200:203], v[48:51]
	v_mfma_f32_16x16x32_bf16 v[36:39], v[176:179], v[208:211], v[36:39]
	v_mfma_f32_16x16x32_bf16 v[32:35], v[184:187], v[208:211], v[32:35]
	v_mfma_f32_16x16x32_bf16 v[12:15], v[176:179], v[216:219], v[12:15]
	v_mfma_f32_16x16x32_bf16 v[8:11], v[184:187], v[216:219], v[8:11]
	s_barrier
; #define PG8_STAGE(bufoff, gbase, voff) do { _Pragma("unroll") for (int _i = 0; _i < 2; ++_i) \
;         __builtin_amdgcn_global_load_lds((const unsigned*)((const char*)(gbase) + (voff)[_i]), (LAS unsigned*)(lds + (bufoff) + ldsw + _i * 8192), 16, 0, 0); } while (0)
; #define PG8_LDA(dst, b, h) do { _Pragma("unroll") for (int m = 0; m < 4; ++m) _Pragma("unroll") for (int k = 0; k < 2; ++k) dst[m][k] = *(const LAS bf16x8*)(lds + PG8_SA(b, h) + aoff + m * 2048 + k * 1024); } while (0)
; #define PG8_LDB(dst, b, h) do { _Pragma("unroll") for (int n = 0; n < 2; ++n) _Pragma("unroll") for (int k = 0; k < 2; ++k) dst[n][k] = *(const LAS bf16x8*)(lds + PG8_SB(b, h) + boff + n * 2048 + k * 1024); } while (0)
; #define PG8_MMA(ai, bj, At, Bt) do { __builtin_amdgcn_s_setprio(1); _Pragma("unroll") for (int m = 0; m < 4; ++m) _Pragma("unroll") for (int n = 0; n < 2; ++n) _Pragma("unroll") for (int k = 0; k < 2; ++k) \
;         acc[ai][bj][m][n] = __builtin_amdgcn_mfma_f32_16x16x32_bf16(Bt[n][k], At[m][k], acc[ai][bj][m][n], 0, 0, 0); __builtin_amdgcn_s_setprio(0); } while (0)
; #define PG8_WAIT_V(n) asm volatile("s_waitcnt vmcnt(" #n ")" ::: "memory")
; #define PG8_WAIT_L(n) asm volatile("s_waitcnt lgkmcnt(" #n ")" ::: "memory")
; #define PG8_BAR __builtin_amdgcn_s_barrier()
; #define PG8_SCHED __builtin_amdgcn_sched_barrier(0)
; template <class Epi>
; __device__ __forceinline__ void gemm_phase(LAS unsigned char* lds, const Gemm g, const StaticOrder& S, const Epi& E) {
;     ...
;             PG8_STAGE(PG8_SB(0, 1), b2 + hstep, voffB);
;             PG8_WAIT_V(6); PG8_BAR; PG8_MMA(1, 1, At, B1); PG8_BAR;
;             PG8_LDB(B0, 1, 0); PG8_SCHED; PG8_LDA(At, 1, 0); PG8_STAGE(PG8_SA(0, 1), a2 + hstep, voffA);
;             PG8_WAIT_L(8); PG8_BAR; PG8_WAIT_L(0); PG8_MMA(0, 0, At, B0); PG8_BAR; PG8_SCHED;
;             PG8_LDB(B1, 1, 1); PG8_STAGE(PG8_SB(1, 0), b3, voffB);
;             PG8_BAR; PG8_WAIT_L(0); PG8_MMA(0, 1, At, B1); PG8_BAR;
;             PG8_LDA(At, 1, 1); PG8_STAGE(PG8_SA(1, 0), a3, voffA);
	s_add_u32 s68, s26, 0x80000
	s_addc_u32 s69, s27, 0
	s_add_i32 s70, s56, s35
	v_lshl_add_u64 v[154:155], s[68:69], 0, v[140:141]
	s_mov_b32 m0, s70
	s_nop 0
	global_load_lds_dwordx4 v[154:155], off
	v_lshl_add_u64 v[154:155], s[68:69], 0, v[136:137]
	s_add_i32 m0, s70, 0x2000
	s_nop 0
	global_load_lds_dwordx4 v[154:155], off
	s_waitcnt vmcnt(6)
	s_barrier
	v_mfma_f32_16x16x32_bf16 v[44:47], v[220:223], v[188:191], v[44:47]
	v_mfma_f32_16x16x32_bf16 v[40:43], v[228:231], v[188:191], v[40:43]
	v_mfma_f32_16x16x32_bf16 v[28:31], v[220:223], v[196:199], v[28:31]
	v_mfma_f32_16x16x32_bf16 v[24:27], v[228:231], v[196:199], v[24:27]
	v_mfma_f32_16x16x32_bf16 v[20:23], v[220:223], v[204:207], v[20:23]
	v_mfma_f32_16x16x32_bf16 v[16:19], v[228:231], v[204:207], v[16:19]
	v_mfma_f32_16x16x32_bf16 v[4:7], v[220:223], v[212:215], v[4:7]
	v_mfma_f32_16x16x32_bf16 v[0:3], v[228:231], v[212:215], v[0:3]
	v_mfma_f32_16x16x32_bf16 v[44:47], v[224:227], v[192:195], v[44:47]
	v_mfma_f32_16x16x32_bf16 v[40:43], v[232:235], v[192:195], v[40:43]
	v_mfma_f32_16x16x32_bf16 v[28:31], v[224:227], v[200:203], v[28:31]
	v_mfma_f32_16x16x32_bf16 v[24:27], v[232:235], v[200:203], v[24:27]
	v_mfma_f32_16x16x32_bf16 v[20:23], v[224:227], v[208:211], v[20:23]
	v_mfma_f32_16x16x32_bf16 v[16:19], v[232:235], v[208:211], v[16:19]
	v_mfma_f32_16x16x32_bf16 v[4:7], v[224:227], v[216:219], v[4:7]
	v_mfma_f32_16x16x32_bf16 v[0:3], v[232:235], v[216:219], v[0:3]
	s_add_i32 s68, 0, 0x18000
	v_add_u32_e32 v144, s68, v135
	s_barrier
	ds_read_b128 v[154:157], v144
	ds_read_b128 v[176:179], v144 offset:1024
	ds_read_b128 v[180:183], v144 offset:2048
	ds_read_b128 v[184:187], v144 offset:3072
	s_add_u32 s28, s28, 0x80000
	s_addc_u32 s29, s29, 0
	s_mov_b32 m0, s44
	v_lshl_add_u64 v[220:221], s[28:29], 0, v[142:143]
	ds_read_b128 v[188:191], v174 offset:32768
	ds_read_b128 v[192:195], v174 offset:33792
	ds_read_b128 v[196:199], v174 offset:34816
	ds_read_b128 v[200:203], v174 offset:35840
	ds_read_b128 v[204:207], v174 offset:36864
	ds_read_b128 v[208:211], v174 offset:37888
	ds_read_b128 v[212:215], v174 offset:38912
	ds_read_b128 v[216:219], v174 offset:39936
	global_load_lds_dwordx4 v[220:221], off
	v_lshl_add_u64 v[220:221], s[28:29], 0, v[138:139]
	s_mov_b32 m0, s45
	s_nop 0
	global_load_lds_dwordx4 v[220:221], off
	s_waitcnt lgkmcnt(8)
	s_barrier
	s_waitcnt lgkmcnt(0)
	s_waitcnt lgkmcnt(0)
	v_mfma_f32_16x16x32_bf16 v[124:127], v[154:157], v[188:191], v[124:127]
	v_mfma_f32_16x16x32_bf16 v[120:123], v[180:183], v[188:191], v[120:123]
	v_mfma_f32_16x16x32_bf16 v[116:119], v[154:157], v[196:199], v[116:119]
	v_mfma_f32_16x16x32_bf16 v[112:115], v[180:183], v[196:199], v[112:115]
	v_mfma_f32_16x16x32_bf16 v[100:103], v[154:157], v[204:207], v[100:103]
	v_mfma_f32_16x16x32_bf16 v[96:99], v[180:183], v[204:207], v[96:99]
	v_mfma_f32_16x16x32_bf16 v[76:79], v[154:157], v[212:215], v[76:79]
	v_mfma_f32_16x16x32_bf16 v[72:75], v[180:183], v[212:215], v[72:75]
	v_mfma_f32_16x16x32_bf16 v[124:127], v[176:179], v[192:195], v[124:127]
	v_mfma_f32_16x16x32_bf16 v[120:123], v[184:187], v[192:195], v[120:123]
	v_mfma_f32_16x16x32_bf16 v[116:119], v[176:179], v[200:203], v[116:119]
	v_mfma_f32_16x16x32_bf16 v[112:115], v[184:187], v[200:203], v[112:115]
	v_mfma_f32_16x16x32_bf16 v[100:103], v[176:179], v[208:211], v[100:103]
	v_mfma_f32_16x16x32_bf16 v[96:99], v[184:187], v[208:211], v[96:99]
	v_mfma_f32_16x16x32_bf16 v[76:79], v[176:179], v[216:219], v[76:79]
	v_mfma_f32_16x16x32_bf16 v[72:75], v[184:187], v[216:219], v[72:75]
	s_barrier
	s_add_i32 s28, 0, 0x1c000
	s_add_i32 s29, s68, s35
	v_add_u32_e32 v144, s28, v135
	v_lshl_add_u64 v[236:237], v[236:237], 0, s[16:17]
	s_mov_b32 m0, s29
	ds_read_b128 v[220:223], v144
	ds_read_b128 v[224:227], v144 offset:1024
	ds_read_b128 v[228:231], v144 offset:2048
	ds_read_b128 v[232:235], v144 offset:3072
	global_load_lds_dwordx4 v[236:237], off
	v_lshl_add_u64 v[236:237], v[238:239], 0, s[16:17]
	s_add_i32 m0, s29, 0x2000
	s_nop 0
	global_load_lds_dwordx4 v[236:237], off
	s_barrier
	s_waitcnt lgkmcnt(0)
	s_waitcnt lgkmcnt(0)
	v_mfma_f32_16x16x32_bf16 v[108:111], v[220:223], v[188:191], v[108:111]
	v_mfma_f32_16x16x32_bf16 v[104:107], v[228:231], v[188:191], v[104:107]
	v_mfma_f32_16x16x32_bf16 v[92:95], v[220:223], v[196:199], v[92:95]
	v_mfma_f32_16x16x32_bf16 v[88:91], v[228:231], v[196:199], v[88:91]
	v_mfma_f32_16x16x32_bf16 v[84:87], v[220:223], v[204:207], v[84:87]
	v_mfma_f32_16x16x32_bf16 v[80:83], v[228:231], v[204:207], v[80:83]
	v_mfma_f32_16x16x32_bf16 v[68:71], v[220:223], v[212:215], v[68:71]
	v_mfma_f32_16x16x32_bf16 v[64:67], v[228:231], v[212:215], v[64:67]
	v_mfma_f32_16x16x32_bf16 v[108:111], v[224:227], v[192:195], v[108:111]
	v_mfma_f32_16x16x32_bf16 v[104:107], v[232:235], v[192:195], v[104:107]
	v_mfma_f32_16x16x32_bf16 v[92:95], v[224:227], v[200:203], v[92:95]
	v_mfma_f32_16x16x32_bf16 v[88:91], v[232:235], v[200:203], v[88:91]
	v_mfma_f32_16x16x32_bf16 v[84:87], v[224:227], v[208:211], v[84:87]
	v_mfma_f32_16x16x32_bf16 v[80:83], v[232:235], v[208:211], v[80:83]
	v_mfma_f32_16x16x32_bf16 v[68:71], v[224:227], v[216:219], v[68:71]
	v_mfma_f32_16x16x32_bf16 v[64:67], v[232:235], v[216:219], v[64:67]
	s_mov_b32 m0, s48
	v_lshl_add_u64 v[236:237], v[240:241], 0, s[16:17]
	s_barrier
	ds_read_b128 v[188:191], v174 offset:49152
	ds_read_b128 v[192:195], v174 offset:50176
	ds_read_b128 v[196:199], v174 offset:51200
	ds_read_b128 v[200:203], v174 offset:52224
	ds_read_b128 v[204:207], v174 offset:53248
	ds_read_b128 v[208:211], v174 offset:54272
	ds_read_b128 v[212:215], v174 offset:55296
	ds_read_b128 v[216:219], v174 offset:56320
	global_load_lds_dwordx4 v[236:237], off
	v_lshl_add_u64 v[236:237], v[242:243], 0, s[16:17]
	s_mov_b32 m0, s49
	s_nop 0
	global_load_lds_dwordx4 v[236:237], off
	s_barrier
; __device__ __forceinline__ unsigned pk_bf16(float lo, float hi) { const f32x2 v = (f32x2){lo, hi}; const bf16v2 b = __builtin_convertvector(v, bf16v2); return __builtin_bit_cast(unsigned, b); }
; #define PG8_STAGE(bufoff, gbase, voff) do { _Pragma("unroll") for (int _i = 0; _i < 2; ++_i) \
;         __builtin_amdgcn_global_load_lds((const unsigned*)((const char*)(gbase) + (voff)[_i]), (LAS unsigned*)(lds + (bufoff) + ldsw + _i * 8192), 16, 0, 0); } while (0)
; #define PG8_WAIT_V(n) asm volatile("s_waitcnt vmcnt(" #n ")" ::: "memory")
; template <class Epi>
; __device__ __forceinline__ void gemm_phase(LAS unsigned char* lds, const Gemm g, const StaticOrder& S, const Epi& E) {
;     ...
;             PG8_BAR; PG8_WAIT_L(0); PG8_MMA(1, 0, At, B0); PG8_BAR; PG8_SCHED;
;             PG8_STAGE(PG8_SB(1, 1), b3 + hstep, voffB);
;             PG8_WAIT_V(6); PG8_BAR; PG8_MMA(1, 1, At, B1); PG8_BAR;
;         }
;         E(acc, cur, wr, wc, fr, fq);
;         if (!has_next) break;
;     __device__ __forceinline__ void operator()(const f32x4 (&acc)[2][2][4][2], const pg8::Unit& u, int wr, int wc, int fr, int fq) const {
;         const int row0 = u.pm * 256 + wr * 64 + fr, col0 = u.pn * 256 + wc * 32 + 8 * fq;
; #pragma unroll
;         for (int ai = 0; ai < 2; ++ai)
; #pragma unroll
;             for (int m = 0; m < 4; ++m) {
;                 const int row = row0 + ai * 128 + m * 16;
;                 bf16_t* rowp = Z + (size_t)row * LDZ + col0;
;                 const bool last = ((row & 63) == 63) && (row >= MP || (row & (SEQ - 1)) == SEQ - 1);
; #pragma unroll
;                 for (int bj = 0; bj < 2; ++bj) {
;                     const f32x4 v0 = acc[ai][bj][m][0], v1 = acc[ai][bj][m][1];
;                     u32x4 w; w.x = pk_bf16(v0[0], v0[1]); w.y = pk_bf16(v0[2], v0[3]); w.z = pk_bf16(v1[0], v1[1]); w.w = pk_bf16(v1[2], v1[3]);
;                     *(u32x4*)(rowp + bj * 128) = w;
;                     if (last) {
;                         const int c = col0 + bj * 128 - ZC_S;
;                         if (c >= 0 && c < NSHIFT) {
;                             float* o = row < MP ? out + O_SHP + (size_t)(row >> 13) * NSHIFT + c : out + O_SHS + (size_t)((row - MP) >> 6) * NSHIFT + c;
;                             *(f32x4*)o = v0; *(f32x4*)(o + 4) = v1;
;                         }
;                     }
;                 }
	s_waitcnt lgkmcnt(0)
	s_waitcnt lgkmcnt(0)
	v_mfma_f32_16x16x32_bf16 v[60:63], v[154:157], v[188:191], v[60:63]
	v_mfma_f32_16x16x32_bf16 v[56:59], v[180:183], v[188:191], v[56:59]
	v_mfma_f32_16x16x32_bf16 v[52:55], v[154:157], v[196:199], v[52:55]
	v_mfma_f32_16x16x32_bf16 v[48:51], v[180:183], v[196:199], v[48:51]
	v_mfma_f32_16x16x32_bf16 v[36:39], v[154:157], v[204:207], v[36:39]
	v_mfma_f32_16x16x32_bf16 v[32:35], v[180:183], v[204:207], v[32:35]
	v_mfma_f32_16x16x32_bf16 v[12:15], v[154:157], v[212:215], v[12:15]
	v_mfma_f32_16x16x32_bf16 v[8:11], v[180:183], v[212:215], v[8:11]
	v_mfma_f32_16x16x32_bf16 v[60:63], v[176:179], v[192:195], v[60:63]
	v_mfma_f32_16x16x32_bf16 v[56:59], v[184:187], v[192:195], v[56:59]
	v_mfma_f32_16x16x32_bf16 v[52:55], v[176:179], v[200:203], v[52:55]
	v_mfma_f32_16x16x32_bf16 v[48:51], v[184:187], v[200:203], v[48:51]
	v_mfma_f32_16x16x32_bf16 v[36:39], v[176:179], v[208:211], v[36:39]
	v_mfma_f32_16x16x32_bf16 v[32:35], v[184:187], v[208:211], v[32:35]
	v_mfma_f32_16x16x32_bf16 v[12:15], v[176:179], v[216:219], v[12:15]
	v_mfma_f32_16x16x32_bf16 v[8:11], v[184:187], v[216:219], v[8:11]
	s_barrier
	s_add_u32 s26, s26, 0x80080
	s_addc_u32 s27, s27, 0
	s_add_i32 s28, s28, s35
	v_lshl_add_u64 v[154:155], s[26:27], 0, v[140:141]
	s_mov_b32 m0, s28
	s_nop 0
	global_load_lds_dwordx4 v[154:155], off
	v_lshl_add_u64 v[154:155], s[26:27], 0, v[136:137]
	s_add_i32 m0, s28, 0x2000
	s_nop 0
	global_load_lds_dwordx4 v[154:155], off
	s_waitcnt vmcnt(6)
	s_barrier
	v_mfma_f32_16x16x32_bf16 v[44:47], v[220:223], v[188:191], v[44:47]
	v_mfma_f32_16x16x32_bf16 v[40:43], v[228:231], v[188:191], v[40:43]
	v_mfma_f32_16x16x32_bf16 v[28:31], v[220:223], v[196:199], v[28:31]
	v_mfma_f32_16x16x32_bf16 v[24:27], v[228:231], v[196:199], v[24:27]
	v_mfma_f32_16x16x32_bf16 v[20:23], v[220:223], v[204:207], v[20:23]
	v_mfma_f32_16x16x32_bf16 v[16:19], v[228:231], v[204:207], v[16:19]
	v_mfma_f32_16x16x32_bf16 v[4:7], v[220:223], v[212:215], v[4:7]
	v_mfma_f32_16x16x32_bf16 v[0:3], v[228:231], v[212:215], v[0:3]
	v_mfma_f32_16x16x32_bf16 v[44:47], v[224:227], v[192:195], v[44:47]
	v_mfma_f32_16x16x32_bf16 v[40:43], v[232:235], v[192:195], v[40:43]
	v_mfma_f32_16x16x32_bf16 v[28:31], v[224:227], v[200:203], v[28:31]
	v_mfma_f32_16x16x32_bf16 v[24:27], v[232:235], v[200:203], v[24:27]
	v_mfma_f32_16x16x32_bf16 v[20:23], v[224:227], v[208:211], v[20:23]
	v_mfma_f32_16x16x32_bf16 v[16:19], v[232:235], v[208:211], v[16:19]
	v_mfma_f32_16x16x32_bf16 v[4:7], v[224:227], v[216:219], v[4:7]
	v_mfma_f32_16x16x32_bf16 v[0:3], v[232:235], v[216:219], v[0:3]
	s_add_i32 s67, s67, 2
	s_add_u32 s12, s12, 0x100
	s_addc_u32 s13, s13, 0
	s_add_u32 s65, s65, 0x100
	s_addc_u32 s66, s66, 0
	s_cmp_gt_u32 s67, 29
	s_barrier
	s_cbranch_scc0 .LBB0_80
	s_lshl_b32 s7, s31, 8
	s_add_i32 s7, s7, s47
	v_lshl_or_b32 v156, s30, 8, v172
	s_add_i32 s12, s7, 0xffff8000
	v_or_b32_e32 v176, s7, v161
	v_ashrrev_i32_e32 v157, 31, v156
	s_lshr_b32 s63, s12, 6
	s_ashr_i32 s12, s7, 13
	v_mov_b64_e32 v[178:179], s[14:15]
	s_mul_i32 s26, s12, 0xc80
	v_mad_i64_i32 v[180:181], s[12:13], v176, s58, v[178:179]
	v_lshlrev_b64 v[154:155], 1, v[156:157]
	v_cvt_pk_bf16_f32 v108, v108, v109
	v_cvt_pk_bf16_f32 v109, v110, v111
	v_cvt_pk_bf16_f32 v110, v104, v105
	v_or_b32_e32 v104, 16, v176
	v_cvt_pk_bf16_f32 v92, v92, v93
	v_cvt_pk_bf16_f32 v93, v94, v95
	v_cvt_pk_bf16_f32 v94, v88, v89
	v_or_b32_e32 v88, 32, v176
	v_cvt_pk_bf16_f32 v84, v84, v85
	v_cvt_pk_bf16_f32 v85, v86, v87
	v_cvt_pk_bf16_f32 v87, v82, v83
	v_or_b32_e32 v82, 48, v176
	v_lshl_add_u64 v[180:181], v[180:181], 0, v[154:155]
	v_cvt_pk_bf16_f32 v111, v106, v107
	v_mad_i64_i32 v[104:105], s[12:13], v104, s58, v[178:179]
	v_mad_i64_i32 v[88:89], s[12:13], v88, s58, v[178:179]
	v_cvt_pk_bf16_f32 v86, v80, v81
	v_mad_i64_i32 v[80:81], s[12:13], v82, s58, v[178:179]
	v_bitop3_b32 v83, v176, s60, 48 bitop3:0xc8
	global_store_dwordx4 v[180:181], v[108:111], off offset:256
	v_cvt_pk_bf16_f32 v95, v90, v91
	v_cmp_lt_i32_e32 vcc, s59, v82
	v_lshl_add_u64 v[108:109], v[104:105], 0, v[154:155]
	v_cmp_eq_u32_e64 s[12:13], s60, v83
	global_store_dwordx4 v[108:109], v[92:95], off offset:256
	s_or_b64 s[12:13], vcc, s[12:13]
	s_mul_hi_u32 s25, s63, 0x3200
	v_lshl_add_u64 v[92:93], v[88:89], 0, v[154:155]
	s_mulk_i32 s63, 0x3200
	s_ashr_i32 s27, s26, 31
	v_cvt_pk_bf16_f32 v124, v124, v125
	v_cvt_pk_bf16_f32 v125, v126, v127
	v_cvt_pk_bf16_f32 v126, v120, v121
	v_cvt_pk_bf16_f32 v127, v122, v123
	v_cvt_pk_bf16_f32 v104, v116, v117
	v_cvt_pk_bf16_f32 v105, v118, v119
	v_cvt_pk_bf16_f32 v106, v112, v113
	v_cvt_pk_bf16_f32 v107, v114, v115
	v_cvt_pk_bf16_f32 v88, v100, v101
	v_cvt_pk_bf16_f32 v89, v102, v103
	v_cvt_pk_bf16_f32 v90, v96, v97
	v_cvt_pk_bf16_f32 v91, v98, v99
	global_store_dwordx4 v[92:93], v[84:87], off offset:256
	v_lshl_add_u64 v[80:81], v[80:81], 0, v[154:155]
	s_and_b64 s[28:29], s[8:9], s[12:13]
	v_cmp_gt_i32_e32 vcc, s50, v82
	v_cvt_pk_bf16_f32 v82, v76, v77
	v_cvt_pk_bf16_f32 v83, v78, v79
	v_cvt_pk_bf16_f32 v84, v72, v73
	v_cvt_pk_bf16_f32 v85, v74, v75
	v_add_u32_e32 v144, 0xfffff400, v156
	global_store_dwordx4 v[180:181], v[124:127], off
	global_store_dwordx4 v[108:109], v[104:107], off
	global_store_dwordx4 v[92:93], v[88:91], off
	global_store_dwordx4 v[80:81], v[82:85], off
	s_and_saveexec_b64 s[30:31], s[28:29]
	s_cbranch_execz .LBB0_84
	v_cmp_gt_u32_e64 s[12:13], s57, v144
	s_and_b64 exec, exec, s[12:13]
	s_cbranch_execz .LBB0_84
	s_lshl_b64 s[12:13], s[26:27], 2
	s_add_u32 s12, s22, s12
	s_addc_u32 s13, s23, s13
	s_add_u32 s64, s51, s63
	s_addc_u32 s65, s52, s25
	v_mov_b32_e32 v82, s65
	v_mov_b32_e32 v83, s13
	v_cndmask_b32_e32 v83, v82, v83, vcc
	v_mov_b32_e32 v82, s64
	v_mov_b32_e32 v84, s12
	v_cndmask_b32_e32 v82, v82, v84, vcc
	v_lshl_add_u64 v[82:83], v[144:145], 2, v[82:83]
	global_store_dwordx4 v[82:83], v[76:79], off
	global_store_dwordx4 v[82:83], v[72:75], off offset:16

; #define PG8_WAIT_V(n) asm volatile("s_waitcnt vmcnt(" #n ")" ::: "memory")
; #define PG8_BAR __builtin_amdgcn_s_barrier()
; template <class Epi>
; __device__ __forceinline__ void gemm_phase(LAS unsigned char* lds, const Gemm g, const StaticOrder& S, const Epi& E) {
;     ...
;     PG8_WAIT_V(0);
;     if (wr == 0) PG8_BAR;
;     PG8_BAR;
.LBB0_95:
	s_setprio 0
	v_readlane_b32 s40, v244, 6
	s_barrier
	v_readlane_b32 s41, v244, 7

; #define PG8_STAGE(bufoff, gbase, voff) do { _Pragma("unroll") for (int _i = 0; _i < 2; ++_i) \
;         __builtin_amdgcn_global_load_lds((const unsigned*)((const char*)(gbase) + (voff)[_i]), (LAS unsigned*)(lds + (bufoff) + ldsw + _i * 8192), 16, 0, 0); } while (0)
; #define PG8_WAIT_V(n) asm volatile("s_waitcnt vmcnt(" #n ")" ::: "memory")
; #define PG8_BAR __builtin_amdgcn_s_barrier()
; template <class Epi>
; __device__ __forceinline__ void gemm_phase(LAS unsigned char* lds, const Gemm g, const StaticOrder& S, const Epi& E) {
;     const int tid = threadIdx.x, wid = __builtin_amdgcn_readfirstlane(tid >> 6), lane = tid & 63, wr = wid >> 2, wc = wid & 3, fr = lane & 15, fq = lane >> 4;
;     const int K = g.K, nt = K / BK;
;     unsigned voffA[2], voffB[2];
; #pragma unroll
;     for (int i = 0; i < 2; ++i) { int R, C; stage_rc(tid * 16 + i * 8192, R, C); const int Rb = Epi::PERM ? ((R & ~31) + perm32(R & 31)) : R;
;         voffA[i] = (unsigned)(R * K + C) * 2u; voffB[i] = (unsigned)(Rb * K + C) * 2u; }
;     const size_t kstep = (size_t)(BK * 2);
;     const size_t hstep = (size_t)HALF * K * 2;
;     const size_t tstep = 2 * hstep;
;     const unsigned ldsw = (unsigned)wid * 1024u;
;     const int aoff = lds_byte(wr * 64 + fr, fq * 8), boff = lds_byte(wc * 32 + fr, fq * 8);
;     ...
;     Unit cur, nxt; int ui = 0;
;     if (!S.next(0, cur)) return;
;     f32x4 acc[2][2][4][2];
; #pragma unroll
;     for (int a = 0; a < 2; ++a)
; #pragma unroll
;         for (int b = 0; b < 2; ++b)
; #pragma unroll
;             for (int m = 0; m < 4; ++m)
; #pragma unroll
;                 for (int n = 0; n < 2; ++n) acc[a][b][m][n] = (f32x4){0.f, 0.f, 0.f, 0.f};
;     bf16x8 At[4][2], B0[2][2], B1[2][2];
;     const char* cA = (const char*)g.A + (size_t)cur.pm * tstep; const char* cB = (const char*)g.Bt + (size_t)cur.pn * tstep;
;     PG8_STAGE(PG8_SB(0, 0), cB, voffB); PG8_STAGE(PG8_SA(0, 0), cA, voffA); PG8_STAGE(PG8_SB(0, 1), cB + hstep, voffB); PG8_STAGE(PG8_SA(0, 1), cA + hstep, voffA);
;     if (wr == 1) PG8_BAR;
;     PG8_WAIT_V(4); PG8_BAR;
;     PG8_STAGE(PG8_SB(1, 0), cB + kstep, voffB); PG8_STAGE(PG8_SA(1, 0), cA + kstep, voffA); PG8_STAGE(PG8_SB(1, 1), cB + hstep + kstep, voffB);
;     PG8_WAIT_V(6); PG8_BAR;
.LBB0_552:
	s_or_b64 exec, exec, s[2:3]
	s_cmpk_gt_i32 s40, 0x43f
	v_readfirstlane_b32 s42, v133
	s_barrier
	s_cbranch_scc1 .LBB0_564
	s_waitcnt vmcnt(2)
	v_and_b32_e32 v0, 4, v169
	v_and_b32_e32 v1, 24, v165
	s_waitcnt vmcnt(0)
	v_add_u32_e32 v8, 0x2000, v166
	v_or3_b32 v0, v0, v168, v1
	v_lshrrev_b32_e32 v1, 7, v8
	s_movk_i32 s8, 0xe0
	v_and_or_b32 v2, v1, s8, v0
	s_movk_i32 s8, 0xf0
	v_bitop3_b32 v9, v166, v167, 48 bitop3:0x6c
	v_and_or_b32 v1, v1, s8, v160
	s_movk_i32 s8, 0x60
	v_or_b32_e32 v3, v9, v159
	v_and_or_b32 v0, v164, s8, v0
	s_movk_i32 s8, 0x70
	s_ashr_i32 s44, s40, 31
	v_lshl_or_b32 v138, v0, 12, v3
	v_and_or_b32 v0, v164, s8, v160
	s_lshr_b32 s8, s44, 29
	s_add_i32 s8, s40, s8
	s_lshr_b32 s12, s42, 6
	s_ashr_i32 s10, s8, 3
	s_and_b32 s8, s8, -8
	s_lshr_b32 s9, s42, 8
	s_lshl_b32 s43, s12, 10
	s_sub_i32 s8, s40, s8
	s_cmp_lt_i32 s8, 0
	s_movk_i32 s45, 0x89
	s_cselect_b32 s11, s45, 0x88
	s_mul_i32 s8, s11, s8
	s_add_i32 s8, s8, s10
	s_ashr_i32 s10, s8, 31
	s_lshr_b32 s10, s10, 26
	s_add_i32 s10, s8, s10
	s_ashr_i32 s11, s10, 6
	s_and_b32 s10, s10, 0xffc0
	s_sub_i32 s10, s8, s10
	s_bfe_i32 s8, s10, 0x80000
	s_bfe_u32 s8, s8, 0x3000c
	s_add_i32 s13, s10, s8
	s_bfe_i32 s8, s13, 0x80000
	s_and_b32 s13, s13, 0xf8
	s_sub_i32 s10, s10, s13
	s_load_dwordx2 s[2:3], s[0:1], 0xc8
	s_load_dwordx2 s[4:5], s[0:1], 0xd8
	s_load_dwordx2 s[6:7], s[0:1], 0xe8
	s_lshl_b32 s11, s11, 3
	s_sext_i32_i16 s8, s8
	s_sext_i32_i8 s10, s10
	s_lshr_b32 s8, s8, 3
	s_add_i32 s20, s11, s10
	s_ashr_i32 s21, s20, 31
	s_bfe_i64 s[14:15], s[8:9], 0x100000
	s_lshl_b64 s[10:11], s[20:21], 20
	s_lshl_b64 s[14:15], s[14:15], 20
	s_waitcnt lgkmcnt(0)
	s_add_u32 s34, s4, s14
	s_addc_u32 s35, s5, s15
	s_add_i32 s21, s43, 0
	s_add_i32 m0, s21, 0x10000
	v_lshl_or_b32 v134, v2, 12, v3
	global_load_lds_dwordx4 v138, s[34:35]
	s_add_i32 m0, s21, 0x12000
	s_add_u32 s30, s2, s10
	v_lshl_or_b32 v140, v0, 12, v3
	global_load_lds_dwordx4 v134, s[34:35]
	s_addc_u32 s31, s3, s11
	s_mov_b32 m0, s21
	s_add_i32 s46, s21, 0x2000
	v_lshl_or_b32 v136, v1, 12, v3
	global_load_lds_dwordx4 v140, s[30:31]
	s_mov_b32 m0, s46
	s_add_u32 s10, s34, 0x80000
	global_load_lds_dwordx4 v136, s[30:31]
	s_addc_u32 s11, s35, 0
	s_add_i32 m0, s21, 0x14000
	v_mov_b32_e32 v139, 0
	global_load_lds_dwordx4 v138, s[10:11]
	s_add_i32 m0, s21, 0x16000
	v_mov_b32_e32 v135, v139
	global_load_lds_dwordx4 v134, s[10:11]
	s_add_u32 s10, s30, 0x80000
	s_addc_u32 s11, s31, 0
	s_add_i32 s47, s21, 0x4000
	s_mov_b32 m0, s47
	s_add_i32 s48, s21, 0x6000
	global_load_lds_dwordx4 v140, s[10:11]
	s_mov_b32 m0, s48
	v_mov_b32_e32 v141, v139
	global_load_lds_dwordx4 v136, s[10:11]
	v_mov_b32_e32 v137, v139
	s_mov_b32 s49, 0
	v_lshl_add_u64 v[6:7], s[34:35], 0, v[138:139]
	v_lshl_add_u64 v[4:5], s[34:35], 0, v[134:135]
	v_lshl_add_u64 v[2:3], s[30:31], 0, v[140:141]
	v_lshl_add_u64 v[0:1], s[30:31], 0, v[136:137]
	s_cmp_lg_u32 s9, 1
	s_mov_b64 s[10:11], 0x80000
	s_cbranch_scc1 .LBB0_555
	s_setprio 1
	s_barrier

; #define PG8_STAGE(bufoff, gbase, voff) do { _Pragma("unroll") for (int _i = 0; _i < 2; ++_i) \
;         __builtin_amdgcn_global_load_lds((const unsigned*)((const char*)(gbase) + (voff)[_i]), (LAS unsigned*)(lds + (bufoff) + ldsw + _i * 8192), 16, 0, 0); } while (0)
; #define PG8_LDA(dst, b, h) do { _Pragma("unroll") for (int m = 0; m < 4; ++m) _Pragma("unroll") for (int k = 0; k < 2; ++k) dst[m][k] = *(const LAS bf16x8*)(lds + PG8_SA(b, h) + aoff + m * 2048 + k * 1024); } while (0)
; #define PG8_LDB(dst, b, h) do { _Pragma("unroll") for (int n = 0; n < 2; ++n) _Pragma("unroll") for (int k = 0; k < 2; ++k) dst[n][k] = *(const LAS bf16x8*)(lds + PG8_SB(b, h) + boff + n * 2048 + k * 1024); } while (0)
; #define PG8_MMA(ai, bj, At, Bt) do { __builtin_amdgcn_s_setprio(1); _Pragma("unroll") for (int m = 0; m < 4; ++m) _Pragma("unroll") for (int n = 0; n < 2; ++n) _Pragma("unroll") for (int k = 0; k < 2; ++k) \
;         acc[ai][bj][m][n] = __builtin_amdgcn_mfma_f32_16x16x32_bf16(Bt[n][k], At[m][k], acc[ai][bj][m][n], 0, 0, 0); __builtin_amdgcn_s_setprio(0); } while (0)
; #define PG8_WAIT_L(n) asm volatile("s_waitcnt lgkmcnt(" #n ")" ::: "memory")
; #define PG8_BAR __builtin_amdgcn_s_barrier()
; #define PG8_SCHED __builtin_amdgcn_sched_barrier(0)
; template <class Epi>
; __device__ __forceinline__ void gemm_phase(LAS unsigned char* lds, const Gemm g, const StaticOrder& S, const Epi& E) {
;     ...
;             PG8_LDB(B0, 0, 0); PG8_SCHED; PG8_LDA(At, 0, 0); PG8_STAGE(PG8_SA(1, 1), a1 + hstep, voffA);
;             PG8_WAIT_L(8); PG8_BAR; PG8_WAIT_L(0); PG8_MMA(0, 0, At, B0); PG8_BAR; PG8_SCHED;
;             PG8_LDB(B1, 0, 1); PG8_STAGE(PG8_SB(0, 0), b2, voffB);
;             PG8_BAR; PG8_WAIT_L(0); PG8_MMA(0, 1, At, B1); PG8_BAR;
;             PG8_LDA(At, 0, 1); PG8_STAGE(PG8_SA(0, 0), a2, voffA);
;             PG8_BAR; PG8_WAIT_L(0); PG8_MMA(1, 0, At, B0); PG8_BAR; PG8_SCHED;
.LBB0_559:
	ds_read_b128 v[156:159], v133
	ds_read_b128 v[160:163], v133 offset:1024
	ds_read_b128 v[164:167], v133 offset:2048
	ds_read_b128 v[168:171], v133 offset:3072
	s_add_u32 s34, s30, 0xfff80080
	s_addc_u32 s35, s31, -1
	s_cmp_eq_u32 s65, 28
	s_cselect_b32 s41, s25, s35
	s_cselect_b32 s40, s61, s34
	s_cselect_b32 s35, s23, s64
	s_cselect_b32 s34, s62, s63
	v_lshl_add_u64 v[204:205], s[30:31], 0, v[142:143]
	s_add_i32 m0, s21, 0xc000
	ds_read_b128 v[172:175], v153
	ds_read_b128 v[176:179], v153 offset:1024
	ds_read_b128 v[180:183], v153 offset:2048
	ds_read_b128 v[184:187], v153 offset:3072
	ds_read_b128 v[188:191], v153 offset:4096
	ds_read_b128 v[192:195], v153 offset:5120
	ds_read_b128 v[196:199], v153 offset:6144
	ds_read_b128 v[200:203], v153 offset:7168
	global_load_lds_dwordx4 v[204:205], off
	v_lshl_add_u64 v[204:205], s[30:31], 0, v[144:145]
	s_add_i32 m0, s21, 0xe000
	s_nop 0
	global_load_lds_dwordx4 v[204:205], off
	s_waitcnt lgkmcnt(8)
	s_barrier
	s_waitcnt lgkmcnt(0)
	s_waitcnt lgkmcnt(0)
	v_mfma_f32_16x16x32_bf16 v[124:127], v[156:159], v[172:175], v[124:127]
	v_mfma_f32_16x16x32_bf16 v[120:123], v[164:167], v[172:175], v[120:123]
	v_mfma_f32_16x16x32_bf16 v[116:119], v[156:159], v[180:183], v[116:119]
	v_mfma_f32_16x16x32_bf16 v[112:115], v[164:167], v[180:183], v[112:115]
	v_mfma_f32_16x16x32_bf16 v[100:103], v[156:159], v[188:191], v[100:103]
	v_mfma_f32_16x16x32_bf16 v[96:99], v[164:167], v[188:191], v[96:99]
	v_mfma_f32_16x16x32_bf16 v[84:87], v[156:159], v[196:199], v[84:87]
	v_mfma_f32_16x16x32_bf16 v[80:83], v[164:167], v[196:199], v[80:83]
	v_mfma_f32_16x16x32_bf16 v[124:127], v[160:163], v[176:179], v[124:127]
	v_mfma_f32_16x16x32_bf16 v[120:123], v[168:171], v[176:179], v[120:123]
	v_mfma_f32_16x16x32_bf16 v[116:119], v[160:163], v[184:187], v[116:119]
	v_mfma_f32_16x16x32_bf16 v[112:115], v[168:171], v[184:187], v[112:115]
	v_mfma_f32_16x16x32_bf16 v[100:103], v[160:163], v[192:195], v[100:103]
	v_mfma_f32_16x16x32_bf16 v[96:99], v[168:171], v[192:195], v[96:99]
	v_mfma_f32_16x16x32_bf16 v[84:87], v[160:163], v[200:203], v[84:87]
	v_mfma_f32_16x16x32_bf16 v[80:83], v[168:171], v[200:203], v[80:83]
	s_barrier
	s_add_i32 s66, s54, s43
	v_lshl_add_u64 v[220:221], s[34:35], 0, v[138:139]
	s_mov_b32 m0, s66
	ds_read_b128 v[204:207], v154
	ds_read_b128 v[208:211], v154 offset:1024
	ds_read_b128 v[212:215], v154 offset:2048
	ds_read_b128 v[216:219], v154 offset:3072
	global_load_lds_dwordx4 v[220:221], off
	v_lshl_add_u64 v[222:223], s[34:35], 0, v[134:135]
	s_add_i32 m0, s66, 0x2000
	s_nop 0
	global_load_lds_dwordx4 v[222:223], off
	s_barrier
	s_waitcnt lgkmcnt(0)
	s_waitcnt lgkmcnt(0)
	v_mfma_f32_16x16x32_bf16 v[108:111], v[204:207], v[172:175], v[108:111]
	v_mfma_f32_16x16x32_bf16 v[104:107], v[212:215], v[172:175], v[104:107]
	v_mfma_f32_16x16x32_bf16 v[92:95], v[204:207], v[180:183], v[92:95]
	v_mfma_f32_16x16x32_bf16 v[88:91], v[212:215], v[180:183], v[88:91]
	v_mfma_f32_16x16x32_bf16 v[76:79], v[204:207], v[188:191], v[76:79]
	v_mfma_f32_16x16x32_bf16 v[72:75], v[212:215], v[188:191], v[72:75]
	v_mfma_f32_16x16x32_bf16 v[68:71], v[204:207], v[196:199], v[68:71]
	v_mfma_f32_16x16x32_bf16 v[64:67], v[212:215], v[196:199], v[64:67]
	v_mfma_f32_16x16x32_bf16 v[108:111], v[208:211], v[176:179], v[108:111]
	v_mfma_f32_16x16x32_bf16 v[104:107], v[216:219], v[176:179], v[104:107]
	v_mfma_f32_16x16x32_bf16 v[92:95], v[208:211], v[184:187], v[92:95]
	v_mfma_f32_16x16x32_bf16 v[88:91], v[216:219], v[184:187], v[88:91]
	v_mfma_f32_16x16x32_bf16 v[76:79], v[208:211], v[192:195], v[76:79]
	v_mfma_f32_16x16x32_bf16 v[72:75], v[216:219], v[192:195], v[72:75]
	v_mfma_f32_16x16x32_bf16 v[68:71], v[208:211], v[200:203], v[68:71]
	v_mfma_f32_16x16x32_bf16 v[64:67], v[216:219], v[200:203], v[64:67]
	s_mov_b32 m0, s21
	v_lshl_add_u64 v[224:225], s[40:41], 0, v[140:141]
	s_barrier
	ds_read_b128 v[172:175], v153 offset:16384
	ds_read_b128 v[176:179], v153 offset:17408
	ds_read_b128 v[180:183], v153 offset:18432
	ds_read_b128 v[184:187], v153 offset:19456
	ds_read_b128 v[188:191], v153 offset:20480
	ds_read_b128 v[192:195], v153 offset:21504
	ds_read_b128 v[196:199], v153 offset:22528
	ds_read_b128 v[200:203], v153 offset:23552
	global_load_lds_dwordx4 v[224:225], off
	v_lshl_add_u64 v[226:227], s[40:41], 0, v[136:137]
	s_mov_b32 m0, s46
	s_nop 0
	global_load_lds_dwordx4 v[226:227], off
	s_barrier
	s_waitcnt lgkmcnt(0)
	s_waitcnt lgkmcnt(0)
	v_mfma_f32_16x16x32_bf16 v[60:63], v[156:159], v[172:175], v[60:63]
	v_mfma_f32_16x16x32_bf16 v[56:59], v[164:167], v[172:175], v[56:59]
	v_mfma_f32_16x16x32_bf16 v[52:55], v[156:159], v[180:183], v[52:55]
	v_mfma_f32_16x16x32_bf16 v[48:51], v[164:167], v[180:183], v[48:51]
	v_mfma_f32_16x16x32_bf16 v[36:39], v[156:159], v[188:191], v[36:39]
	v_mfma_f32_16x16x32_bf16 v[32:35], v[164:167], v[188:191], v[32:35]
	v_mfma_f32_16x16x32_bf16 v[20:23], v[156:159], v[196:199], v[20:23]
	v_mfma_f32_16x16x32_bf16 v[16:19], v[164:167], v[196:199], v[16:19]
	v_mfma_f32_16x16x32_bf16 v[60:63], v[160:163], v[176:179], v[60:63]
	v_mfma_f32_16x16x32_bf16 v[56:59], v[168:171], v[176:179], v[56:59]
	v_mfma_f32_16x16x32_bf16 v[52:55], v[160:163], v[184:187], v[52:55]
	v_mfma_f32_16x16x32_bf16 v[48:51], v[168:171], v[184:187], v[48:51]
	v_mfma_f32_16x16x32_bf16 v[36:39], v[160:163], v[192:195], v[36:39]
	v_mfma_f32_16x16x32_bf16 v[32:35], v[168:171], v[192:195], v[32:35]
	v_mfma_f32_16x16x32_bf16 v[20:23], v[160:163], v[200:203], v[20:23]
	v_mfma_f32_16x16x32_bf16 v[16:19], v[168:171], v[200:203], v[16:19]
	s_barrier
; #define PG8_STAGE(bufoff, gbase, voff) do { _Pragma("unroll") for (int _i = 0; _i < 2; ++_i) \
;         __builtin_amdgcn_global_load_lds((const unsigned*)((const char*)(gbase) + (voff)[_i]), (LAS unsigned*)(lds + (bufoff) + ldsw + _i * 8192), 16, 0, 0); } while (0)
; #define PG8_LDA(dst, b, h) do { _Pragma("unroll") for (int m = 0; m < 4; ++m) _Pragma("unroll") for (int k = 0; k < 2; ++k) dst[m][k] = *(const LAS bf16x8*)(lds + PG8_SA(b, h) + aoff + m * 2048 + k * 1024); } while (0)
; #define PG8_LDB(dst, b, h) do { _Pragma("unroll") for (int n = 0; n < 2; ++n) _Pragma("unroll") for (int k = 0; k < 2; ++k) dst[n][k] = *(const LAS bf16x8*)(lds + PG8_SB(b, h) + boff + n * 2048 + k * 1024); } while (0)
; #define PG8_MMA(ai, bj, At, Bt) do { __builtin_amdgcn_s_setprio(1); _Pragma("unroll") for (int m = 0; m < 4; ++m) _Pragma("unroll") for (int n = 0; n < 2; ++n) _Pragma("unroll") for (int k = 0; k < 2; ++k) \
;         acc[ai][bj][m][n] = __builtin_amdgcn_mfma_f32_16x16x32_bf16(Bt[n][k], At[m][k], acc[ai][bj][m][n], 0, 0, 0); __builtin_amdgcn_s_setprio(0); } while (0)
; #define PG8_WAIT_V(n) asm volatile("s_waitcnt vmcnt(" #n ")" ::: "memory")
; #define PG8_WAIT_L(n) asm volatile("s_waitcnt lgkmcnt(" #n ")" ::: "memory")
; #define PG8_BAR __builtin_amdgcn_s_barrier()
; #define PG8_SCHED __builtin_amdgcn_sched_barrier(0)
; template <class Epi>
; __device__ __forceinline__ void gemm_phase(LAS unsigned char* lds, const Gemm g, const StaticOrder& S, const Epi& E) {
;     ...
;             PG8_STAGE(PG8_SB(0, 1), b2 + hstep, voffB);
;             PG8_WAIT_V(6); PG8_BAR; PG8_MMA(1, 1, At, B1); PG8_BAR;
;             PG8_LDB(B0, 1, 0); PG8_SCHED; PG8_LDA(At, 1, 0); PG8_STAGE(PG8_SA(0, 1), a2 + hstep, voffA);
;             PG8_WAIT_L(8); PG8_BAR; PG8_WAIT_L(0); PG8_MMA(0, 0, At, B0); PG8_BAR; PG8_SCHED;
;             PG8_LDB(B1, 1, 1); PG8_STAGE(PG8_SB(1, 0), b3, voffB);
;             PG8_BAR; PG8_WAIT_L(0); PG8_MMA(0, 1, At, B1); PG8_BAR;
;             PG8_LDA(At, 1, 1); PG8_STAGE(PG8_SA(1, 0), a3, voffA);
	s_add_u32 s66, s34, 0x80000
	s_addc_u32 s67, s35, 0
	s_add_i32 s68, s55, s43
	v_lshl_add_u64 v[156:157], s[66:67], 0, v[138:139]
	s_mov_b32 m0, s68
	s_nop 0
	global_load_lds_dwordx4 v[156:157], off
	v_lshl_add_u64 v[156:157], s[66:67], 0, v[134:135]
	s_add_i32 m0, s68, 0x2000
	s_nop 0
	global_load_lds_dwordx4 v[156:157], off
	s_waitcnt vmcnt(6)
	s_barrier
	v_mfma_f32_16x16x32_bf16 v[44:47], v[204:207], v[172:175], v[44:47]
	v_mfma_f32_16x16x32_bf16 v[40:43], v[212:215], v[172:175], v[40:43]
	v_mfma_f32_16x16x32_bf16 v[28:31], v[204:207], v[180:183], v[28:31]
	v_mfma_f32_16x16x32_bf16 v[24:27], v[212:215], v[180:183], v[24:27]
	v_mfma_f32_16x16x32_bf16 v[12:15], v[204:207], v[188:191], v[12:15]
	v_mfma_f32_16x16x32_bf16 v[8:11], v[212:215], v[188:191], v[8:11]
	v_mfma_f32_16x16x32_bf16 v[4:7], v[204:207], v[196:199], v[4:7]
	v_mfma_f32_16x16x32_bf16 v[0:3], v[212:215], v[196:199], v[0:3]
	v_mfma_f32_16x16x32_bf16 v[44:47], v[208:211], v[176:179], v[44:47]
	v_mfma_f32_16x16x32_bf16 v[40:43], v[216:219], v[176:179], v[40:43]
	v_mfma_f32_16x16x32_bf16 v[28:31], v[208:211], v[184:187], v[28:31]
	v_mfma_f32_16x16x32_bf16 v[24:27], v[216:219], v[184:187], v[24:27]
	v_mfma_f32_16x16x32_bf16 v[12:15], v[208:211], v[192:195], v[12:15]
	v_mfma_f32_16x16x32_bf16 v[8:11], v[216:219], v[192:195], v[8:11]
	v_mfma_f32_16x16x32_bf16 v[4:7], v[208:211], v[200:203], v[4:7]
	v_mfma_f32_16x16x32_bf16 v[0:3], v[216:219], v[200:203], v[0:3]
	s_add_i32 s66, 0, 0x18000
	v_add_u32_e32 v155, s66, v151
	s_barrier
	ds_read_b128 v[156:159], v155
	ds_read_b128 v[160:163], v155 offset:1024
	ds_read_b128 v[164:167], v155 offset:2048
	ds_read_b128 v[168:171], v155 offset:3072
	s_add_u32 s40, s40, 0x80000
	s_addc_u32 s41, s41, 0
	s_mov_b32 m0, s47
	v_lshl_add_u64 v[204:205], s[40:41], 0, v[140:141]
	ds_read_b128 v[172:175], v153 offset:32768
	ds_read_b128 v[176:179], v153 offset:33792
	ds_read_b128 v[180:183], v153 offset:34816
	ds_read_b128 v[184:187], v153 offset:35840
	ds_read_b128 v[188:191], v153 offset:36864
	ds_read_b128 v[192:195], v153 offset:37888
	ds_read_b128 v[196:199], v153 offset:38912
	ds_read_b128 v[200:203], v153 offset:39936
	global_load_lds_dwordx4 v[204:205], off
	v_lshl_add_u64 v[204:205], s[40:41], 0, v[136:137]
	s_mov_b32 m0, s48
	s_nop 0
	global_load_lds_dwordx4 v[204:205], off
	s_waitcnt lgkmcnt(8)
	s_barrier
	s_waitcnt lgkmcnt(0)
	s_waitcnt lgkmcnt(0)
	v_mfma_f32_16x16x32_bf16 v[124:127], v[156:159], v[172:175], v[124:127]
	v_mfma_f32_16x16x32_bf16 v[120:123], v[164:167], v[172:175], v[120:123]
	v_mfma_f32_16x16x32_bf16 v[116:119], v[156:159], v[180:183], v[116:119]
	v_mfma_f32_16x16x32_bf16 v[112:115], v[164:167], v[180:183], v[112:115]
	v_mfma_f32_16x16x32_bf16 v[100:103], v[156:159], v[188:191], v[100:103]
	v_mfma_f32_16x16x32_bf16 v[96:99], v[164:167], v[188:191], v[96:99]
	v_mfma_f32_16x16x32_bf16 v[84:87], v[156:159], v[196:199], v[84:87]
	v_mfma_f32_16x16x32_bf16 v[80:83], v[164:167], v[196:199], v[80:83]
	v_mfma_f32_16x16x32_bf16 v[124:127], v[160:163], v[176:179], v[124:127]
	v_mfma_f32_16x16x32_bf16 v[120:123], v[168:171], v[176:179], v[120:123]
	v_mfma_f32_16x16x32_bf16 v[116:119], v[160:163], v[184:187], v[116:119]
	v_mfma_f32_16x16x32_bf16 v[112:115], v[168:171], v[184:187], v[112:115]
	v_mfma_f32_16x16x32_bf16 v[100:103], v[160:163], v[192:195], v[100:103]
	v_mfma_f32_16x16x32_bf16 v[96:99], v[168:171], v[192:195], v[96:99]
	v_mfma_f32_16x16x32_bf16 v[84:87], v[160:163], v[200:203], v[84:87]
	v_mfma_f32_16x16x32_bf16 v[80:83], v[168:171], v[200:203], v[80:83]
	s_barrier
	s_add_i32 s40, 0, 0x1c000
	s_add_i32 s41, s66, s43
	v_add_u32_e32 v155, s40, v151
	v_lshl_add_u64 v[220:221], v[220:221], 0, s[12:13]
	s_mov_b32 m0, s41
	ds_read_b128 v[204:207], v155
	ds_read_b128 v[208:211], v155 offset:1024
	ds_read_b128 v[212:215], v155 offset:2048
	ds_read_b128 v[216:219], v155 offset:3072
	global_load_lds_dwordx4 v[220:221], off
	v_lshl_add_u64 v[220:221], v[222:223], 0, s[12:13]
	s_add_i32 m0, s41, 0x2000
	s_nop 0
	global_load_lds_dwordx4 v[220:221], off
	s_barrier
	s_waitcnt lgkmcnt(0)
	s_waitcnt lgkmcnt(0)
	v_mfma_f32_16x16x32_bf16 v[108:111], v[204:207], v[172:175], v[108:111]
	v_mfma_f32_16x16x32_bf16 v[104:107], v[212:215], v[172:175], v[104:107]
	v_mfma_f32_16x16x32_bf16 v[92:95], v[204:207], v[180:183], v[92:95]
	v_mfma_f32_16x16x32_bf16 v[88:91], v[212:215], v[180:183], v[88:91]
	v_mfma_f32_16x16x32_bf16 v[76:79], v[204:207], v[188:191], v[76:79]
	v_mfma_f32_16x16x32_bf16 v[72:75], v[212:215], v[188:191], v[72:75]
	v_mfma_f32_16x16x32_bf16 v[68:71], v[204:207], v[196:199], v[68:71]
	v_mfma_f32_16x16x32_bf16 v[64:67], v[212:215], v[196:199], v[64:67]
	v_mfma_f32_16x16x32_bf16 v[108:111], v[208:211], v[176:179], v[108:111]
	v_mfma_f32_16x16x32_bf16 v[104:107], v[216:219], v[176:179], v[104:107]
	v_mfma_f32_16x16x32_bf16 v[92:95], v[208:211], v[184:187], v[92:95]
	v_mfma_f32_16x16x32_bf16 v[88:91], v[216:219], v[184:187], v[88:91]
	v_mfma_f32_16x16x32_bf16 v[76:79], v[208:211], v[192:195], v[76:79]
	v_mfma_f32_16x16x32_bf16 v[72:75], v[216:219], v[192:195], v[72:75]
	v_mfma_f32_16x16x32_bf16 v[68:71], v[208:211], v[200:203], v[68:71]
	v_mfma_f32_16x16x32_bf16 v[64:67], v[216:219], v[200:203], v[64:67]
	s_mov_b32 m0, s50
	v_lshl_add_u64 v[220:221], v[224:225], 0, s[12:13]
	s_barrier
	ds_read_b128 v[172:175], v153 offset:49152
	ds_read_b128 v[176:179], v153 offset:50176
	ds_read_b128 v[180:183], v153 offset:51200
	ds_read_b128 v[184:187], v153 offset:52224
	ds_read_b128 v[188:191], v153 offset:53248
	ds_read_b128 v[192:195], v153 offset:54272
	ds_read_b128 v[196:199], v153 offset:55296
	ds_read_b128 v[200:203], v153 offset:56320
	global_load_lds_dwordx4 v[220:221], off
	v_lshl_add_u64 v[220:221], v[226:227], 0, s[12:13]
	s_mov_b32 m0, s51
	s_nop 0
	global_load_lds_dwordx4 v[220:221], off
	s_barrier
; #define PG8_STAGE(bufoff, gbase, voff) do { _Pragma("unroll") for (int _i = 0; _i < 2; ++_i) \
;         __builtin_amdgcn_global_load_lds((const unsigned*)((const char*)(gbase) + (voff)[_i]), (LAS unsigned*)(lds + (bufoff) + ldsw + _i * 8192), 16, 0, 0); } while (0)
; #define PG8_MMA(ai, bj, At, Bt) do { __builtin_amdgcn_s_setprio(1); _Pragma("unroll") for (int m = 0; m < 4; ++m) _Pragma("unroll") for (int n = 0; n < 2; ++n) _Pragma("unroll") for (int k = 0; k < 2; ++k) \
;         acc[ai][bj][m][n] = __builtin_amdgcn_mfma_f32_16x16x32_bf16(Bt[n][k], At[m][k], acc[ai][bj][m][n], 0, 0, 0); __builtin_amdgcn_s_setprio(0); } while (0)
; #define PG8_WAIT_V(n) asm volatile("s_waitcnt vmcnt(" #n ")" ::: "memory")
; #define PG8_WAIT_L(n) asm volatile("s_waitcnt lgkmcnt(" #n ")" ::: "memory")
; #define PG8_BAR __builtin_amdgcn_s_barrier()
; #define PG8_SCHED __builtin_amdgcn_sched_barrier(0)
; template <class Epi>
; __device__ __forceinline__ void gemm_phase(LAS unsigned char* lds, const Gemm g, const StaticOrder& S, const Epi& E) {
;     ...
;             PG8_BAR; PG8_WAIT_L(0); PG8_MMA(1, 0, At, B0); PG8_BAR; PG8_SCHED;
;             PG8_STAGE(PG8_SB(1, 1), b3 + hstep, voffB);
;             PG8_WAIT_V(6); PG8_BAR; PG8_MMA(1, 1, At, B1); PG8_BAR;
;         }
	s_waitcnt lgkmcnt(0)
	s_waitcnt lgkmcnt(0)
	v_mfma_f32_16x16x32_bf16 v[60:63], v[156:159], v[172:175], v[60:63]
	v_mfma_f32_16x16x32_bf16 v[56:59], v[164:167], v[172:175], v[56:59]
	v_mfma_f32_16x16x32_bf16 v[52:55], v[156:159], v[180:183], v[52:55]
	v_mfma_f32_16x16x32_bf16 v[48:51], v[164:167], v[180:183], v[48:51]
	v_mfma_f32_16x16x32_bf16 v[36:39], v[156:159], v[188:191], v[36:39]
	v_mfma_f32_16x16x32_bf16 v[32:35], v[164:167], v[188:191], v[32:35]
	v_mfma_f32_16x16x32_bf16 v[20:23], v[156:159], v[196:199], v[20:23]
	v_mfma_f32_16x16x32_bf16 v[16:19], v[164:167], v[196:199], v[16:19]
	v_mfma_f32_16x16x32_bf16 v[60:63], v[160:163], v[176:179], v[60:63]
	v_mfma_f32_16x16x32_bf16 v[56:59], v[168:171], v[176:179], v[56:59]
	v_mfma_f32_16x16x32_bf16 v[52:55], v[160:163], v[184:187], v[52:55]
	v_mfma_f32_16x16x32_bf16 v[48:51], v[168:171], v[184:187], v[48:51]
	v_mfma_f32_16x16x32_bf16 v[36:39], v[160:163], v[192:195], v[36:39]
	v_mfma_f32_16x16x32_bf16 v[32:35], v[168:171], v[192:195], v[32:35]
	v_mfma_f32_16x16x32_bf16 v[20:23], v[160:163], v[200:203], v[20:23]
	v_mfma_f32_16x16x32_bf16 v[16:19], v[168:171], v[200:203], v[16:19]
	s_barrier
	s_add_u32 s34, s34, 0x80080
	s_addc_u32 s35, s35, 0
	s_add_i32 s40, s40, s43
	v_lshl_add_u64 v[156:157], s[34:35], 0, v[138:139]
	s_mov_b32 m0, s40
	s_nop 0
	global_load_lds_dwordx4 v[156:157], off
	v_lshl_add_u64 v[156:157], s[34:35], 0, v[134:135]
	s_add_i32 m0, s40, 0x2000
	s_nop 0
	global_load_lds_dwordx4 v[156:157], off
	s_waitcnt vmcnt(6)
	s_barrier
	v_mfma_f32_16x16x32_bf16 v[44:47], v[204:207], v[172:175], v[44:47]
	v_mfma_f32_16x16x32_bf16 v[40:43], v[212:215], v[172:175], v[40:43]
	v_mfma_f32_16x16x32_bf16 v[28:31], v[204:207], v[180:183], v[28:31]
	v_mfma_f32_16x16x32_bf16 v[24:27], v[212:215], v[180:183], v[24:27]
	v_mfma_f32_16x16x32_bf16 v[12:15], v[204:207], v[188:191], v[12:15]
	v_mfma_f32_16x16x32_bf16 v[8:11], v[212:215], v[188:191], v[8:11]
	v_mfma_f32_16x16x32_bf16 v[4:7], v[204:207], v[196:199], v[4:7]
	v_mfma_f32_16x16x32_bf16 v[0:3], v[212:215], v[196:199], v[0:3]
	v_mfma_f32_16x16x32_bf16 v[44:47], v[208:211], v[176:179], v[44:47]
	v_mfma_f32_16x16x32_bf16 v[40:43], v[216:219], v[176:179], v[40:43]
	v_mfma_f32_16x16x32_bf16 v[28:31], v[208:211], v[184:187], v[28:31]
	v_mfma_f32_16x16x32_bf16 v[24:27], v[216:219], v[184:187], v[24:27]
	v_mfma_f32_16x16x32_bf16 v[12:15], v[208:211], v[192:195], v[12:15]
	v_mfma_f32_16x16x32_bf16 v[8:11], v[216:219], v[192:195], v[8:11]
	v_mfma_f32_16x16x32_bf16 v[4:7], v[208:211], v[200:203], v[4:7]
	v_mfma_f32_16x16x32_bf16 v[0:3], v[216:219], v[200:203], v[0:3]
	s_add_i32 s65, s65, 2
	s_add_u32 s30, s30, 0x100
	s_addc_u32 s31, s31, 0
	s_add_u32 s63, s63, 0x100
	s_addc_u32 s64, s64, 0
	s_cmp_gt_u32 s65, 29
	s_barrier
	s_cbranch_scc0 .LBB0_559
; __device__ __forceinline__ unsigned pk_bf16(float lo, float hi) { const f32x2 v = (f32x2){lo, hi}; const bf16v2 b = __builtin_convertvector(v, bf16v2); return __builtin_bit_cast(unsigned, b); }
; template <class Epi>
; __device__ __forceinline__ void gemm_phase(LAS unsigned char* lds, const Gemm g, const StaticOrder& S, const Epi& E) {
;     ...
;         E(acc, cur, wr, wc, fr, fq);
;         if (!has_next) break;
; #pragma unroll
;         for (int a = 0; a < 2; ++a)
; #pragma unroll
;             for (int b = 0; b < 2; ++b)
; #pragma unroll
;                 for (int m = 0; m < 4; ++m)
; #pragma unroll
;                     for (int n = 0; n < 2; ++n) acc[a][b][m][n] = (f32x4){0.f, 0.f, 0.f, 0.f};
;         cur = nxt; cA = nA; cB = nB; ++ui;
;     __device__ __forceinline__ void operator()(const f32x4 (&acc)[2][2][4][2], const pg8::Unit& u, int wr, int wc, int fr, int fq) const {
;     ...
;                 const int row = row0 + ai * 128 + m * 16;
;                 bf16_t* orow = yb + (size_t)row * DM + col0;
; #pragma unroll
;                 for (int bj = 0; bj < 2; ++bj) {
;                     const f32x4 v0 = acc[ai][bj][m][0], v1 = acc[ai][bj][m][1];
;                     *(u32x4*)(orow + bj * 128) = (u32x4){pk_bf16(v0[0], v0[1]), pk_bf16(v0[2], v0[3]), pk_bf16(v1[0], v1[1]), pk_bf16(v1[2], v1[3])};
;                 }
;             }
	v_lshl_add_u32 v156, s20, 8, v150
	v_lshl_or_b32 v158, s60, 8, v152
	v_ashrrev_i32_e32 v157, 31, v156
	v_ashrrev_i32_e32 v159, 31, v158
	v_lshlrev_b64 v[160:161], 12, v[156:157]
	v_lshl_add_u64 v[160:161], s[6:7], 0, v[160:161]
	v_lshlrev_b64 v[158:159], 1, v[158:159]
	v_lshl_add_u64 v[160:161], v[160:161], 0, v[158:159]
	v_cvt_pk_bf16_f32 v60, v60, v61
	v_cvt_pk_bf16_f32 v61, v62, v63
	v_cvt_pk_bf16_f32 v62, v56, v57
	v_add_co_u32_e32 v56, vcc, s56, v160
	v_cvt_pk_bf16_f32 v68, v68, v69
	v_cvt_pk_bf16_f32 v69, v70, v71
	v_cvt_pk_bf16_f32 v70, v64, v65
	v_lshl_add_u64 v[64:65], v[160:161], 0, s[10:11]
	v_addc_co_u32_e32 v57, vcc, 0, v161, vcc
	v_cvt_pk_bf16_f32 v44, v44, v45
	v_cvt_pk_bf16_f32 v45, v46, v47
	v_cvt_pk_bf16_f32 v46, v40, v41
	v_cvt_pk_bf16_f32 v47, v42, v43
	v_cvt_pk_bf16_f32 v108, v108, v109
	v_cvt_pk_bf16_f32 v109, v110, v111
	v_cvt_pk_bf16_f32 v110, v104, v105
	v_or_b32_e32 v104, 16, v156
	global_store_dwordx4 v[64:65], v[44:47], off offset:256
	v_ashrrev_i32_e32 v105, 31, v104
	v_cvt_pk_bf16_f32 v92, v92, v93
	v_add_co_u32_e32 v46, vcc, s57, v160
	v_cvt_pk_bf16_f32 v93, v94, v95
	v_cvt_pk_bf16_f32 v94, v88, v89
	v_or_b32_e32 v88, 32, v156
	v_lshl_add_u64 v[44:45], v[160:161], 0, s[14:15]
	v_addc_co_u32_e32 v47, vcc, 0, v161, vcc
	v_cvt_pk_bf16_f32 v28, v28, v29
	v_cvt_pk_bf16_f32 v29, v30, v31
	v_cvt_pk_bf16_f32 v30, v24, v25
	v_cvt_pk_bf16_f32 v31, v26, v27
	v_lshlrev_b64 v[104:105], 12, v[104:105]
	v_ashrrev_i32_e32 v89, 31, v88
	v_cvt_pk_bf16_f32 v76, v76, v77
	v_cvt_pk_bf16_f32 v77, v78, v79
	v_cvt_pk_bf16_f32 v78, v72, v73
	v_or_b32_e32 v72, 48, v156
	global_store_dwordx4 v[44:45], v[28:31], off offset:256
	v_cvt_pk_bf16_f32 v111, v106, v107
	v_lshl_add_u64 v[104:105], s[6:7], 0, v[104:105]
	v_add_co_u32_e32 v30, vcc, s58, v160
	v_lshlrev_b64 v[88:89], 12, v[88:89]
	v_ashrrev_i32_e32 v73, 31, v72
	v_lshl_add_u64 v[28:29], v[160:161], 0, s[16:17]
	v_addc_co_u32_e32 v31, vcc, 0, v161, vcc
	v_cvt_pk_bf16_f32 v12, v12, v13
	v_cvt_pk_bf16_f32 v13, v14, v15
	v_cvt_pk_bf16_f32 v14, v8, v9
	v_cvt_pk_bf16_f32 v15, v10, v11
	global_store_dwordx4 v[160:161], v[108:111], off offset:256
	v_cvt_pk_bf16_f32 v95, v90, v91
	v_lshl_add_u64 v[88:89], s[6:7], 0, v[88:89]
	v_lshl_add_u64 v[108:109], v[104:105], 0, v[158:159]
	v_lshlrev_b64 v[72:73], 12, v[72:73]
	global_store_dwordx4 v[28:29], v[12:15], off offset:256
	global_store_dwordx4 v[108:109], v[92:95], off offset:256
	v_cvt_pk_bf16_f32 v79, v74, v75
	v_add_co_u32_e32 v14, vcc, s59, v160
	v_lshl_add_u64 v[92:93], v[88:89], 0, v[158:159]
	v_lshl_add_u64 v[72:73], s[6:7], 0, v[72:73]
	v_addc_co_u32_e32 v15, vcc, 0, v161, vcc
	v_cvt_pk_bf16_f32 v124, v124, v125
	v_cvt_pk_bf16_f32 v125, v126, v127
	v_cvt_pk_bf16_f32 v126, v120, v121
	v_cvt_pk_bf16_f32 v127, v122, v123
	v_cvt_pk_bf16_f32 v104, v116, v117
	v_cvt_pk_bf16_f32 v105, v118, v119
	v_cvt_pk_bf16_f32 v106, v112, v113
	v_cvt_pk_bf16_f32 v107, v114, v115
	v_cvt_pk_bf16_f32 v88, v100, v101
	v_cvt_pk_bf16_f32 v89, v102, v103
	v_cvt_pk_bf16_f32 v90, v96, v97
	v_cvt_pk_bf16_f32 v91, v98, v99
	global_store_dwordx4 v[92:93], v[76:79], off offset:256
	v_cvt_pk_bf16_f32 v74, v80, v81
	v_cvt_pk_bf16_f32 v75, v82, v83
	v_lshl_add_u64 v[76:77], v[72:73], 0, v[158:159]
	v_cvt_pk_bf16_f32 v72, v84, v85
	v_cvt_pk_bf16_f32 v73, v86, v87
	v_cvt_pk_bf16_f32 v71, v66, v67
	v_cvt_pk_bf16_f32 v63, v58, v59
	v_cvt_pk_bf16_f32 v40, v52, v53
	v_cvt_pk_bf16_f32 v41, v54, v55
	v_cvt_pk_bf16_f32 v42, v48, v49
	v_cvt_pk_bf16_f32 v43, v50, v51
	v_cvt_pk_bf16_f32 v24, v36, v37
	v_cvt_pk_bf16_f32 v25, v38, v39
	v_cvt_pk_bf16_f32 v26, v32, v33
	v_cvt_pk_bf16_f32 v27, v34, v35
	v_lshl_add_u64 v[12:13], v[160:161], 0, s[18:19]
	v_cvt_pk_bf16_f32 v8, v20, v21
	v_cvt_pk_bf16_f32 v9, v22, v23
	v_cvt_pk_bf16_f32 v10, v16, v17
	v_cvt_pk_bf16_f32 v11, v18, v19
	v_cvt_pk_bf16_f32 v4, v4, v5
	v_cvt_pk_bf16_f32 v5, v6, v7
	v_cvt_pk_bf16_f32 v6, v0, v1
	v_cvt_pk_bf16_f32 v7, v2, v3
	s_and_b64 vcc, exec, s[8:9]
	s_mov_b32 s60, s22
	s_mov_b32 s20, s24
	s_mov_b64 s[34:35], s[28:29]
	s_mov_b64 s[30:31], s[26:27]
	s_mov_b32 s40, s70
	global_store_dwordx4 v[160:161], v[124:127], off
	global_store_dwordx4 v[108:109], v[104:107], off
	global_store_dwordx4 v[92:93], v[88:91], off
	global_store_dwordx4 v[76:77], v[72:75], off
	global_store_dwordx4 v[76:77], v[68:71], off offset:256
	global_store_dwordx4 v[56:57], v[60:63], off
	global_store_dwordx4 v[46:47], v[40:43], off
	global_store_dwordx4 v[30:31], v[24:27], off
	global_store_dwordx4 v[14:15], v[8:11], off
	global_store_dwordx4 v[12:13], v[4:7], off offset:256
	s_cbranch_vccnz .Lg2_exit
	s_cmp_lg_u32 s49, 4
	s_cbranch_scc1 .LBB0_556
	s_waitcnt vmcnt(0)
	s_barrier
	s_lshr_b32 s8, s42, 6
	s_cmp_lg_u32 s8, 4
	s_cbranch_scc1 .LBB0_556
	buffer_wbl2 sc1
	s_waitcnt vmcnt(0)
	s_mov_b64 s[8:9], exec
	s_mov_b64 exec, 1
	v_mov_b32_e32 v0, 0
	v_mov_b32_e32 v1, 1
	global_atomic_add v0, v1, s[36:37] offset:256
	s_mov_b64 exec, s[8:9]
	s_branch .LBB0_556

; #define PG8_WAIT_V(n) asm volatile("s_waitcnt vmcnt(" #n ")" ::: "memory")
; #define PG8_BAR __builtin_amdgcn_s_barrier()
; template <class Epi>
; __device__ __forceinline__ void gemm_phase(LAS unsigned char* lds, const Gemm g, const StaticOrder& S, const Epi& E) {
;     ...
;     PG8_WAIT_V(0);
;     if (wr == 0) PG8_BAR;
;     PG8_BAR;
.LBB0_563:
	s_setprio 0
	s_barrier
	s_cmp_lt_u32 s40, 64
	s_cbranch_scc1 .LBB0_564
	s_cmp_gt_u32 s42, 63
	s_cbranch_scc1 .Lfin1_sync
	buffer_wbl2 sc1
	s_waitcnt vmcnt(0)
	s_mov_b64 s[2:3], exec
	s_mov_b64 exec, 1
	v_mov_b32_e32 v0, 0
	v_mov_b32_e32 v1, 1
	global_atomic_add v0, v1, s[36:37] offset:256
	s_mov_b32 s4, 0
